# band rel-bias LDS reads batched; attention ticket atomic wait deferred to use; XCD-leader releases XGEN before its own buffer_inv
# speedup vs baseline: 1.0414x; 1.0414x over previous
; __device__ __forceinline__ unsigned xb_ld(unsigned* p)              { return __hip_atomic_load(p, __ATOMIC_RELAXED, __HIP_MEMORY_SCOPE_AGENT); }
; __device__ __forceinline__ unsigned xb_add(unsigned* p, unsigned v) { return __hip_atomic_fetch_add(p, v, __ATOMIC_RELAXED, __HIP_MEMORY_SCOPE_AGENT); }
; #define XB_SPIN(cond, bar) do { unsigned _sp = 0; while (cond) { __builtin_amdgcn_s_sleep(1); \
;     if ((++_sp & 255u) == 0u) { if (xb_ld(&(bar)[XB_TMO])) break; if (_sp > XB_SPIN_CAP) { atomicAdd(&(bar)[XB_TMO], 1u); break; } } } } while (0)
; __device__ __forceinline__ void xcd_barrier(const XcdBarrier& b, bool leader_thread) {
;     ...
;         const unsigned old = xb_add(&bar[XB_XSUB(b.x)], 1u);
;         const unsigned gen = old / nloc;
;         if (old + 1u == (gen + 1u) * nloc) {
;             __builtin_amdgcn_fence(__ATOMIC_RELEASE, "agent");
;             asm volatile("s_waitcnt vmcnt(0)" ::: "memory");
;             const unsigned og = xb_add(&bar[XB_TOP], 1u);
;             const unsigned tg = og / nx;
;             if (og + 1u == (tg + 1u) * nx) xb_add(&bar[XB_TOPGEN], 1u);
;             else XB_SPIN(xb_ld(&bar[XB_TOPGEN]) == tg, bar);
;             __builtin_amdgcn_fence(__ATOMIC_ACQUIRE, "agent");
;             xb_add(&bar[XB_XGEN(b.x)], 1u);
;             asm volatile("s_waitcnt vmcnt(0)" ::: "memory");
.LBB0_171:
	s_or_b64 exec, exec, s[4:5]
	s_mov_b64 s[4:5], exec
	v_mbcnt_lo_u32_b32 v0, s4, 0
	v_mbcnt_hi_u32_b32 v0, s5, v0
	v_cmp_eq_u32_e32 vcc, 0, v0
	s_waitcnt vmcnt(0)
	s_and_saveexec_b64 s[6:7], vcc
	s_cbranch_execz .LBB0_173
	s_bcnt1_i32_b64 s2, s[4:5]
	v_mov_b32_e32 v0, s2
	v_readlane_b32 s2, v252, 55
	v_readlane_b32 s3, v252, 56
	s_nop 4
	global_atomic_add v1, v0, s[2:3]
.LBB0_173:
	s_or_b64 exec, exec, s[6:7]
	buffer_inv sc1
	s_waitcnt vmcnt(0)

; __device__ __forceinline__ unsigned xb_add(unsigned* p, unsigned v) { return __hip_atomic_fetch_add(p, v, __ATOMIC_RELAXED, __HIP_MEMORY_SCOPE_AGENT); }
; __device__ __forceinline__ void xcd_barrier(const XcdBarrier& b, bool leader_thread) {
;     ...
;             __builtin_amdgcn_fence(__ATOMIC_ACQUIRE, "agent");
;             xb_add(&bar[XB_XGEN(b.x)], 1u);
;             asm volatile("s_waitcnt vmcnt(0)" ::: "memory");
.LBB0_355:
	s_or_b64 exec, exec, s[8:9]
	s_mov_b64 s[8:9], exec
	v_mbcnt_lo_u32_b32 v0, s8, 0
	v_mbcnt_hi_u32_b32 v0, s9, v0
	v_cmp_eq_u32_e32 vcc, 0, v0
	s_waitcnt vmcnt(0)
	s_and_saveexec_b64 s[10:11], vcc
	s_cbranch_execz .LBB0_357
	s_bcnt1_i32_b64 s3, s[8:9]
	v_readlane_b32 s6, v252, 55
	v_mov_b32_e32 v0, s3
	v_readlane_b32 s7, v252, 56
	s_nop 4
	global_atomic_add v1, v0, s[6:7]
.LBB0_357:
	s_or_b64 exec, exec, s[10:11]
	buffer_inv sc1
	s_waitcnt vmcnt(0)

; __device__ __forceinline__ unsigned xb_add(unsigned* p, unsigned v) { return __hip_atomic_fetch_add(p, v, __ATOMIC_RELAXED, __HIP_MEMORY_SCOPE_AGENT); }
; __device__ __forceinline__ void xcd_barrier(const XcdBarrier& b, bool leader_thread) {
;     ...
;             __builtin_amdgcn_fence(__ATOMIC_ACQUIRE, "agent");
;             xb_add(&bar[XB_XGEN(b.x)], 1u);
;             asm volatile("s_waitcnt vmcnt(0)" ::: "memory");
.LBB0_579:
	s_or_b64 exec, exec, s[6:7]
	s_mov_b64 s[6:7], exec
	v_mbcnt_lo_u32_b32 v0, s6, 0
	v_mbcnt_hi_u32_b32 v0, s7, v0
	v_cmp_eq_u32_e32 vcc, 0, v0
	s_waitcnt vmcnt(0)
	s_and_saveexec_b64 s[10:11], vcc
	s_cbranch_execz .LBB0_581
	s_bcnt1_i32_b64 s3, s[6:7]
	v_readlane_b32 s6, v252, 55
	v_mov_b32_e32 v0, s3
	v_readlane_b32 s7, v252, 56
	s_nop 4
	global_atomic_add v1, v0, s[6:7]

; __device__ __forceinline__ int lane_id_v() { int l; asm volatile("v_mbcnt_lo_u32_b32 %0, -1, 0\n\tv_mbcnt_hi_u32_b32 %0, -1, %0" : "=v"(l)); return l; }
; #define LAS __attribute__((address_space(3)))
; template <int TYPE> __device__ __forceinline__ int unit(const P& p, LAS unsigned char* lds, int b, int h, int qb, int wave0, bool pre, unsigned nx, int G,
;         u32x4& kA, u32x4& vA, u32x4& k2A, float& cbA, u32x4& kB, u32x4& vB, u32x4& k2B, float& cbB) {
;     ...
;     int tid_ = wave0 * 64 + lane_id_v(); asm volatile("" : "+v"(tid_));
;     const int tid = tid_, lane = tid & 63, r32 = lane & 31, hi = lane >> 5; const int w = __builtin_amdgcn_readfirstlane(tid >> 6);
;     const size_t rowbase = (size_t)b * SEQ;
;     const bf16* Qp = (TYPE == 0) ? p.QA : (TYPE == 1) ? p.QB : p.QC; const bf16* Kp = (TYPE == 0) ? p.KA : (TYPE == 1) ? p.KBN : p.KC; const bf16* Vp = (TYPE == 0) ? p.VA : (TYPE == 1) ? p.VB : p.VC;
;     bf16* Yp = (TYPE == 0) ? p.YA : (TYPE == 1) ? p.YB : p.YC;
;     constexpr int QPITCH = (TYPE == 1) ? 768 : 512;
;     const int n = 4 * qb + (w >> 1);
;     const int u_lo = (TYPE == 2) ? (4 * qb - 8 > 0 ? 4 * qb - 8 : 0) : 0, u_hi = 4 * qb + 3;
;     const int w_lo = (TYPE == 2) ? (n - 8 > 0 ? n - 8 : 0) : 0, w_hi = n;
;     bf16x8 qr[ND0];
;     { const bf16* qrow = Qp + (rowbase + 256 * qb + 32 * w + r32) * QPITCH + h * DQK + 8 * hi;
; #pragma unroll
;       for (int d0 = 0; d0 < ND0; ++d0) qr[d0] = *(const bf16x8*)(qrow + 16 * d0); }
;     if (TYPE == 2) { LAS float* rt = (LAS float*)(lds + RELOFF); for (int i = tid; i < 592; i += 512) rt[i] = p.relb[h * 513 + (i < 512 ? i : 512)] * LOG2E; }
; __device__ __forceinline__ void phase(const P& p, LAS unsigned char* lds, unsigned* ctr, int wave0, int tid) {
;     ...
;     while (i < 1536) {
;         unsigned nx = 0u;
;         if (tid == 0) nx = atomicAdd(ctr, 1u);
;         const int qb = 7 - i / 192, rem = i % 192, ty = rem / 64, bh = rem % 64, b = bh >> 3, h = bh & 7;
;         if (ty == 0) i = unit<1>(p, lds, b, h, qb, wave0, pre, nx, G, kA, vA, k2A, cbA, kB, vB, k2B, cbB);
;         else if (ty == 1) i = unit<0>(p, lds, b, h, qb, wave0, pre, nx, G, kA, vA, k2A, cbA, kB, vB, k2B, cbB);
;         else i = unit<2>(p, lds, b, h, qb, wave0, pre, nx, G, kA, vA, k2A, cbA, kB, vB, k2B, cbB);
.LBB0_589:
	v_mov_b32_e32 v219, 0
	v_mov_b32_e32 v250, 0
	s_mov_b64 s[4:5], exec
	v_readlane_b32 s2, v255, 9
	v_readlane_b32 s3, v255, 10
	s_and_b64 s[2:3], s[4:5], s[2:3]
	s_mov_b64 exec, s[2:3]
	s_cbranch_execz .LBB0_593
	s_mov_b64 s[8:9], exec
	v_mbcnt_lo_u32_b32 v0, s8, 0
	v_mbcnt_hi_u32_b32 v0, s9, v0
	v_cmp_eq_u32_e32 vcc, 0, v0
	s_and_saveexec_b64 s[6:7], vcc
	s_cbranch_execz .LBB0_592
	s_bcnt1_i32_b64 s2, s[8:9]
	v_mov_b32_e32 v2, s2
	v_readlane_b32 s2, v255, 7
	v_readlane_b32 s3, v255, 8
	s_nop 4
	global_atomic_add v250, v1, v2, s[2:3] sc0
.LBB0_592:
	s_or_b64 exec, exec, s[6:7]
.LBB0_593:
	s_or_b64 exec, exec, s[4:5]
	s_xor_b64 s[0:1], s[0:1], -1
	v_writelane_b32 v254, s0, 34
	s_nop 1
	v_writelane_b32 v254, s1, 35
	s_mul_hi_i32 s0, s25, 0xd5555555
	s_lshr_b32 s1, s0, 31
	s_ashr_i32 s28, s0, 5
	s_mul_hi_i32 s0, s25, 0x2aaaaaab
	s_add_i32 s28, s28, s1
	s_lshr_b32 s1, s0, 31
	s_lshr_b32 s0, s0, 5
	s_add_i32 s0, s0, s1
	s_mulk_i32 s0, 0xc0
	s_sub_i32 s0, s25, s0
	s_bfe_u32 s1, s0, 0x60019
	s_add_i32 s1, s0, s1
	s_and_b32 s1, s1, 0xffc0
	s_sub_i32 s10, s0, s1
	s_sext_i32_i16 s1, s10
	s_add_i32 s33, s28, 7
	s_ashr_i32 s40, s1, 3
	s_and_b32 s24, s1, 7
	s_add_i32 s1, s0, 63
	s_cmpk_gt_u32 s1, 0x7e
	s_cbranch_scc0 .LBB0_629
	s_andn2_b32 s0, s0, 63
	s_cmp_lg_u32 s0, 64
	s_cbranch_scc0 .LBB0_630
	v_readlane_b32 s0, v251, 2
	s_ashr_i32 s41, s40, 31
	v_mbcnt_lo_u32_b32 v0, -1, 0
	v_mbcnt_hi_u32_b32 v0, -1, v0
	s_lshl_b32 s3, s33, 8
	v_add_u32_e32 v206, s0, v0
	s_lshl_b64 s[0:1], s[40:41], 11
	s_add_u32 s3, s0, s3
	v_readfirstlane_b32 s2, v206
	s_addc_u32 s6, s1, 0
	s_ashr_i32 s11, s2, 1
	v_and_b32_e32 v242, 31, v206
	s_and_b32 s4, s11, 0xffffffe0
	s_ashr_i32 s5, s4, 31
	v_or_b32_e32 v2, s3, v242
	v_mov_b32_e32 v3, s6
	v_lshl_add_u64 v[10:11], v[2:3], 0, s[4:5]
	v_readlane_b32 s4, v254, 59
	v_lshlrev_b64 v[2:3], 10, v[10:11]
	v_readlane_b32 s5, v254, 60
	v_bfe_u32 v12, v206, 5, 1
	s_lshl_b32 s44, s24, 7
	v_lshl_add_u64 v[2:3], s[4:5], 0, v[2:3]
	v_lshl_add_u64 v[2:3], v[2:3], 0, s[44:45]
	v_lshlrev_b32_e32 v204, 4, v12
	v_mov_b32_e32 v205, v1
	v_lshl_add_u64 v[2:3], v[2:3], 0, v[204:205]
	global_load_dwordx4 v[132:135], v[2:3], off
	global_load_dwordx4 v[128:131], v[2:3], off offset:32
	global_load_dwordx4 v[124:127], v[2:3], off offset:64
	global_load_dwordx4 v[120:123], v[2:3], off offset:96
	s_movk_i32 s3, 0x250
	v_cmp_gt_i32_e32 vcc, s3, v206
	s_and_saveexec_b64 s[4:5], vcc
	s_cbranch_execz .LBB0_603
	v_max_i32_e32 v0, 0x50, v206
	v_sub_u32_e32 v0, v0, v206
	v_add_u32_e32 v0, 0x1ff, v0
	s_movk_i32 s6, 0x1ff
	s_mul_i32 s3, s24, 0x201
	v_cmp_lt_u32_e32 vcc, s6, v0
	s_mov_b64 s[8:9], -1
	v_mov_b32_e32 v2, v206
	s_and_saveexec_b64 s[6:7], vcc
	s_cbranch_execz .LBB0_600
	v_lshrrev_b32_e32 v0, 9, v0
	v_add_u32_e32 v0, 1, v0
	v_and_b32_e32 v4, 0xfffffe, v0
	v_add_u32_e32 v207, 0x200, v206
	v_readlane_b32 s8, v254, 14
	s_mov_b32 s25, s3
	v_mov_b32_e32 v6, v4
	v_lshl_add_u32 v5, v206, 2, s8
	s_mov_b64 s[8:9], 0
	v_mov_b64_e32 v[2:3], v[206:207]

; #define ATT_LOAD(t, S) do { const int tl_ = (t) < u_hi ? (t) : u_hi;     \
;         k##S = *(const u32x4*)(kg + (size_t)tl_ * 64 * 512); v##S = *(const u32x4*)(vg + (size_t)tl_ * 64 * 512); \
;         if (TYPE == 1) k2##S = *(const u32x4*)(krg + (size_t)tl_ * 64 * 32); if (TYPE == 0) cb##S = cg_[tl_ * 64]; } while (0)
; template <int TYPE> __device__ __forceinline__ int unit(const P& p, LAS unsigned char* lds, int b, int h, int qb, int wave0, bool pre, unsigned nx, int G,
;         u32x4& kA, u32x4& vA, u32x4& k2A, float& cbA, u32x4& kB, u32x4& vB, u32x4& k2B, float& cbB) {
;     ...
;     float m_run = 0.f, l_run = 0.f; f32x16 o0 = {}, o1 = {};
;     f32x16 negm;
; #pragma unroll
;     for (int r = 0; r < 16; ++r) negm[r] = 0.f;
;     if (!pre) { ATT_LOAD(u_lo, A); ATT_LOAD(u_lo + 1, B); }
;     ATT_STORE(0, A);
;     __syncthreads();
;     const int qrel = 32 * (w & 1) + r32;
;     int t = u_lo;
;     ...
;         if (t == u_lo && tid == 0) tk[0] = G + (int)nx;
.LBB0_605:
	s_movk_i32 s4, 0x90
	v_lshlrev_b64 v[220:221], 9, v[10:11]
	v_mul_lo_u32 v10, v226, s4
	v_add_u32_e32 v10, 0, v10
	s_ashr_i32 s2, s2, 7
	v_add_u32_e32 v240, v10, v0
	v_lshrrev_b32_e32 v244, 2, v206
	s_waitcnt vmcnt(3)
	ds_write_b128 v240, v[6:9]
	v_mad_u64_u32 v[6:7], s[0:1], v226, 48, v[10:11]
	v_mad_u32_u24 v205, v242, s4, 0
	v_lshlrev_b32_e32 v218, 2, v12
	s_lshl_b32 s4, s28, 10
	s_lshl_b32 s5, s2, 8
	v_and_b32_e32 v14, 63, v206
	v_add_u32_e32 v241, v6, v0
	v_and_or_b32 v0, v244, 3, v218
	s_add_i32 s4, s4, s5
	s_lshl_b32 s5, s11, 2
	v_mad_u32_u24 v207, v0, s27, 0
	v_and_b32_e32 v0, 16, v206
	v_lshlrev_b32_e32 v224, 2, v14
	s_and_b32 s5, s5, 0x80
	v_and_or_b32 v0, v224, 12, v0
	s_or_b32 s4, s4, s5
	v_lshlrev_b32_e32 v243, 1, v0
	v_lshl_or_b32 v0, v242, 2, s4
	v_sub_u32_e32 v0, v0, v204
	s_lshl_b32 s4, s9, 8
	v_subrev_u32_e32 v0, s4, v0
	v_readlane_b32 s4, v254, 15
	s_add_i32 s7, s2, s8
	s_max_i32 s3, s7, 8
	v_add_u32_e32 v247, s4, v0
	s_lshl_b32 s4, s28, 2
	s_add_i32 s2, s2, s4
	v_mov_b32_e32 v14, v1
	v_mov_b32_e32 v15, v1
	v_lshlrev_b32_e32 v245, 3, v13
	s_waitcnt vmcnt(2)
	ds_write_b128 v241, v[2:5] offset:26624
	s_sub_i32 s2, s2, s9
	s_sub_i32 s41, s3, s9
	v_mov_b32_e32 v0, v1
	v_mov_b32_e32 v2, v1
	v_mov_b32_e32 v3, v1
	v_mov_b32_e32 v4, v1
	v_mov_b32_e32 v5, v1
	v_mov_b32_e32 v6, v1
	v_mov_b32_e32 v7, v1
	v_mov_b32_e32 v8, v1
	v_mov_b32_e32 v9, v1
	v_mov_b32_e32 v10, v1
	v_mov_b32_e32 v11, v1
	v_mov_b32_e32 v12, v1
	v_mov_b32_e32 v13, v1
	v_mov_b64_e32 v[46:47], v[14:15]
	v_mov_b64_e32 v[30:31], v[14:15]
	v_mov_b64_e32 v[62:63], v[14:15]
	s_add_i32 s6, s3, -8
	s_mov_b32 s29, 0
	v_cmp_eq_u32_e64 s[0:1], 0, v206
	s_waitcnt vmcnt(0)
	v_add_u32_e32 v246, s26, v250
	s_add_i32 s38, s2, 28
	s_add_i32 s39, s41, -8
	s_add_i32 s41, s41, -9
	v_mov_b32_e32 v222, 0
	v_mov_b64_e32 v[44:45], v[12:13]
	v_mov_b64_e32 v[42:43], v[10:11]
	v_mov_b64_e32 v[40:41], v[8:9]
	v_mov_b64_e32 v[38:39], v[6:7]
	v_mov_b64_e32 v[36:37], v[4:5]
	v_mov_b64_e32 v[34:35], v[2:3]
	v_mov_b64_e32 v[32:33], v[0:1]
	v_mov_b64_e32 v[28:29], v[12:13]
	v_mov_b64_e32 v[26:27], v[10:11]
	v_mov_b64_e32 v[24:25], v[8:9]
	v_mov_b64_e32 v[22:23], v[6:7]
	v_mov_b64_e32 v[20:21], v[4:5]
	v_mov_b64_e32 v[18:19], v[2:3]
	v_mov_b64_e32 v[16:17], v[0:1]
	v_mov_b64_e32 v[60:61], v[12:13]
	v_mov_b64_e32 v[58:59], v[10:11]
	v_mov_b64_e32 v[56:57], v[8:9]
	v_mov_b64_e32 v[54:55], v[6:7]
	v_mov_b64_e32 v[52:53], v[4:5]
	v_mov_b64_e32 v[50:51], v[2:3]
	v_mov_b64_e32 v[48:49], v[0:1]
	v_mov_b32_e32 v225, 0
	s_waitcnt lgkmcnt(0)
	s_barrier
	s_branch .LBB0_607

; #define LAS __attribute__((address_space(3)))
; template <int TYPE, int ND0, int KSTR> __device__ __forceinline__ void tile(LAS unsigned char* lds, int buf, int t, int w_lo, int w_hi, int n, int qrel, int lane, int r32, int hi,
;         const bf16x8 (&qr)[ND0], float& m_run, float& l_run, f32x16& o0, f32x16& o1, f32x16& negm) {
;     ...
;     for (int d0 = 0; d0 < ND0; ++d0) {
;         p0 = __builtin_amdgcn_mfma_f32_32x32x16_bf16(ka[d0], qr[d0], p0, 0, 0, 0);
;         p1 = __builtin_amdgcn_mfma_f32_32x32x16_bf16(kc[d0], qr[d0], p1, 0, 0, 0);
;     }
;     ...
;     if (TYPE == 2 && rel < 5) {
;         const LAS float* rb = (const LAS float*)(lds + RELOFF) + (qrel + 64 * rel + 256 - 4 * hi - 59);
; #pragma unroll
;         for (int r = 0; r < 16; ++r) { p0[r] += rb[59 - ((r & 3) + 8 * (r >> 2))]; p1[r] += rb[27 - ((r & 3) + 8 * (r >> 2))]; }
;     }
.LBB0_610:
	s_waitcnt lgkmcnt(14)
	s_nop 0
	v_mfma_f32_32x32x16_bf16 v[80:95], v[196:199], v[132:135], v[64:79]
	s_cmp_gt_i32 s38, 4
	v_mfma_f32_32x32x16_bf16 v[64:79], v[200:203], v[132:135], v[64:79]
	v_mfma_f32_32x32x16_bf16 v[80:95], v[184:187], v[128:131], v[80:95]
	v_mfma_f32_32x32x16_bf16 v[64:79], v[188:191], v[128:131], v[64:79]
	s_waitcnt vmcnt(3)
	v_mfma_f32_32x32x16_bf16 v[80:95], v[180:183], v[124:127], v[80:95]
	v_mfma_f32_32x32x16_bf16 v[64:79], v[192:195], v[124:127], v[64:79]
	s_waitcnt vmcnt(2)
	v_mfma_f32_32x32x16_bf16 v[80:95], v[176:179], v[120:123], v[80:95]
	v_mfma_f32_32x32x16_bf16 v[64:79], v[172:175], v[120:123], v[64:79]
	s_cbranch_scc1 .LBB0_612
	ds_read2_b32 v[196:197], v247 offset0:122 offset1:123
	ds_read2_b32 v[198:199], v247 offset0:90 offset1:91
	ds_read2_b32 v[200:201], v247 offset0:120 offset1:121
	ds_read2_b32 v[202:203], v247 offset0:88 offset1:89
	ds_read2_b32 v[184:185], v247 offset0:114 offset1:115
	ds_read2_b32 v[186:187], v247 offset0:82 offset1:83
	ds_read2_b32 v[188:189], v247 offset0:112 offset1:113
	ds_read2_b32 v[190:191], v247 offset0:80 offset1:81
	ds_read2_b32 v[180:181], v247 offset0:106 offset1:107
	ds_read2_b32 v[182:183], v247 offset0:74 offset1:75
	ds_read2_b32 v[192:193], v247 offset0:104 offset1:105
	ds_read2_b32 v[194:195], v247 offset0:72 offset1:73
	ds_read2_b32 v[176:177], v247 offset0:98 offset1:99
	ds_read2_b32 v[178:179], v247 offset0:66 offset1:67
	ds_read2_b32 v[172:173], v247 offset0:96 offset1:97
	ds_read2_b32 v[174:175], v247 offset0:64 offset1:65
	s_waitcnt lgkmcnt(15)
	s_nop 7
	v_pk_add_f32 v[80:81], v[80:81], v[196:197] op_sel:[0,1] op_sel_hi:[1,0]
	s_waitcnt lgkmcnt(14)
	v_pk_add_f32 v[64:65], v[64:65], v[198:199] op_sel:[0,1] op_sel_hi:[1,0]
	s_waitcnt lgkmcnt(13)
	v_pk_add_f32 v[82:83], v[82:83], v[200:201] op_sel:[0,1] op_sel_hi:[1,0]
	s_waitcnt lgkmcnt(12)
	v_pk_add_f32 v[66:67], v[66:67], v[202:203] op_sel:[0,1] op_sel_hi:[1,0]
	s_waitcnt lgkmcnt(11)
	v_pk_add_f32 v[84:85], v[84:85], v[184:185] op_sel:[0,1] op_sel_hi:[1,0]
	s_waitcnt lgkmcnt(10)
	v_pk_add_f32 v[68:69], v[68:69], v[186:187] op_sel:[0,1] op_sel_hi:[1,0]
	s_waitcnt lgkmcnt(9)
	v_pk_add_f32 v[86:87], v[86:87], v[188:189] op_sel:[0,1] op_sel_hi:[1,0]
	s_waitcnt lgkmcnt(8)
	v_pk_add_f32 v[70:71], v[70:71], v[190:191] op_sel:[0,1] op_sel_hi:[1,0]
	s_waitcnt lgkmcnt(7)
	v_pk_add_f32 v[88:89], v[88:89], v[180:181] op_sel:[0,1] op_sel_hi:[1,0]
	s_waitcnt lgkmcnt(6)
	v_pk_add_f32 v[72:73], v[72:73], v[182:183] op_sel:[0,1] op_sel_hi:[1,0]
	s_waitcnt lgkmcnt(5)
	v_pk_add_f32 v[90:91], v[90:91], v[192:193] op_sel:[0,1] op_sel_hi:[1,0]
	s_waitcnt lgkmcnt(4)
	v_pk_add_f32 v[74:75], v[74:75], v[194:195] op_sel:[0,1] op_sel_hi:[1,0]
	s_waitcnt lgkmcnt(3)
	v_pk_add_f32 v[92:93], v[92:93], v[176:177] op_sel:[0,1] op_sel_hi:[1,0]
	s_waitcnt lgkmcnt(2)
	v_pk_add_f32 v[76:77], v[76:77], v[178:179] op_sel:[0,1] op_sel_hi:[1,0]
	s_waitcnt lgkmcnt(1)
	v_pk_add_f32 v[94:95], v[94:95], v[172:173] op_sel:[0,1] op_sel_hi:[1,0]
	s_waitcnt lgkmcnt(0)
	v_pk_add_f32 v[78:79], v[78:79], v[174:175] op_sel:[0,1] op_sel_hi:[1,0]

; #define LAS __attribute__((address_space(3)))
; template <int TYPE, int ND0, int KSTR> __device__ __forceinline__ void tile(LAS unsigned char* lds, int buf, int t, int w_lo, int w_hi, int n, int qrel, int lane, int r32, int hi,
;         const bf16x8 (&qr)[ND0], float& m_run, float& l_run, f32x16& o0, f32x16& o1, f32x16& negm) {
;     ...
;     for (int d0 = 0; d0 < ND0; ++d0) {
;         p0 = __builtin_amdgcn_mfma_f32_32x32x16_bf16(ka[d0], qr[d0], p0, 0, 0, 0);
;         p1 = __builtin_amdgcn_mfma_f32_32x32x16_bf16(kc[d0], qr[d0], p1, 0, 0, 0);
;     }
;     ...
;     if (TYPE == 2 && rel < 5) {
;         const LAS float* rb = (const LAS float*)(lds + RELOFF) + (qrel + 64 * rel + 256 - 4 * hi - 59);
; #pragma unroll
;         for (int r = 0; r < 16; ++r) { p0[r] += rb[59 - ((r & 3) + 8 * (r >> 2))]; p1[r] += rb[27 - ((r & 3) + 8 * (r >> 2))]; }
;     }
.LBB0_620:
	s_waitcnt lgkmcnt(14)
	s_nop 0
	v_mfma_f32_32x32x16_bf16 v[80:95], v[196:199], v[132:135], v[64:79]
	s_cmp_gt_i32 s2, 4
	v_mfma_f32_32x32x16_bf16 v[64:79], v[200:203], v[132:135], v[64:79]
	v_mfma_f32_32x32x16_bf16 v[80:95], v[184:187], v[128:131], v[80:95]
	v_mfma_f32_32x32x16_bf16 v[64:79], v[188:191], v[128:131], v[64:79]
	v_mfma_f32_32x32x16_bf16 v[80:95], v[180:183], v[124:127], v[80:95]
	v_mfma_f32_32x32x16_bf16 v[64:79], v[192:195], v[124:127], v[64:79]
	v_mfma_f32_32x32x16_bf16 v[80:95], v[176:179], v[120:123], v[80:95]
	v_mfma_f32_32x32x16_bf16 v[64:79], v[172:175], v[120:123], v[64:79]
	s_cbranch_scc1 .LBB0_622
	ds_read2_b32 v[196:197], v247 offset0:58 offset1:59
	ds_read2_b32 v[198:199], v247 offset0:26 offset1:27
	ds_read2_b32 v[200:201], v247 offset0:56 offset1:57
	ds_read2_b32 v[202:203], v247 offset0:24 offset1:25
	ds_read2_b32 v[184:185], v247 offset0:50 offset1:51
	ds_read2_b32 v[186:187], v247 offset0:18 offset1:19
	ds_read2_b32 v[188:189], v247 offset0:48 offset1:49
	ds_read2_b32 v[190:191], v247 offset0:16 offset1:17
	ds_read2_b32 v[180:181], v247 offset0:42 offset1:43
	ds_read2_b32 v[182:183], v247 offset0:10 offset1:11
	ds_read2_b32 v[192:193], v247 offset0:40 offset1:41
	ds_read2_b32 v[194:195], v247 offset0:8 offset1:9
	ds_read2_b32 v[176:177], v247 offset0:34 offset1:35
	ds_read2_b32 v[178:179], v247 offset0:2 offset1:3
	ds_read2_b32 v[172:173], v247 offset0:32 offset1:33
	ds_read2_b32 v[174:175], v247 offset1:1
	s_waitcnt lgkmcnt(15)
	s_nop 7
	v_pk_add_f32 v[80:81], v[80:81], v[196:197] op_sel:[0,1] op_sel_hi:[1,0]
	s_waitcnt lgkmcnt(14)
	v_pk_add_f32 v[64:65], v[64:65], v[198:199] op_sel:[0,1] op_sel_hi:[1,0]
	s_waitcnt lgkmcnt(13)
	v_pk_add_f32 v[82:83], v[82:83], v[200:201] op_sel:[0,1] op_sel_hi:[1,0]
	s_waitcnt lgkmcnt(12)
	v_pk_add_f32 v[66:67], v[66:67], v[202:203] op_sel:[0,1] op_sel_hi:[1,0]
	s_waitcnt lgkmcnt(11)
	v_pk_add_f32 v[84:85], v[84:85], v[184:185] op_sel:[0,1] op_sel_hi:[1,0]
	s_waitcnt lgkmcnt(10)
	v_pk_add_f32 v[68:69], v[68:69], v[186:187] op_sel:[0,1] op_sel_hi:[1,0]
	s_waitcnt lgkmcnt(9)
	v_pk_add_f32 v[86:87], v[86:87], v[188:189] op_sel:[0,1] op_sel_hi:[1,0]
	s_waitcnt lgkmcnt(8)
	v_pk_add_f32 v[70:71], v[70:71], v[190:191] op_sel:[0,1] op_sel_hi:[1,0]
	s_waitcnt lgkmcnt(7)
	v_pk_add_f32 v[88:89], v[88:89], v[180:181] op_sel:[0,1] op_sel_hi:[1,0]
	s_waitcnt lgkmcnt(6)
	v_pk_add_f32 v[72:73], v[72:73], v[182:183] op_sel:[0,1] op_sel_hi:[1,0]
	s_waitcnt lgkmcnt(5)
	v_pk_add_f32 v[90:91], v[90:91], v[192:193] op_sel:[0,1] op_sel_hi:[1,0]
	s_waitcnt lgkmcnt(4)
	v_pk_add_f32 v[74:75], v[74:75], v[194:195] op_sel:[0,1] op_sel_hi:[1,0]
	s_waitcnt lgkmcnt(3)
	v_pk_add_f32 v[92:93], v[92:93], v[176:177] op_sel:[0,1] op_sel_hi:[1,0]
	s_waitcnt lgkmcnt(2)
	v_pk_add_f32 v[76:77], v[76:77], v[178:179] op_sel:[0,1] op_sel_hi:[1,0]
	s_waitcnt lgkmcnt(1)
	v_pk_add_f32 v[94:95], v[94:95], v[172:173] op_sel:[0,1] op_sel_hi:[1,0]
	s_waitcnt lgkmcnt(0)
	v_pk_add_f32 v[78:79], v[78:79], v[174:175] op_sel:[0,1] op_sel_hi:[1,0]

; __device__ __forceinline__ int crow(int r, int hi) { return (r & 3) + 8 * (r >> 2) + 4 * hi; }
; #define ATT_LOAD(t, S) do { const int tl_ = (t) < u_hi ? (t) : u_hi;     \
;         k##S = *(const u32x4*)(kg + (size_t)tl_ * 64 * 512); v##S = *(const u32x4*)(vg + (size_t)tl_ * 64 * 512); \
;         if (TYPE == 1) k2##S = *(const u32x4*)(krg + (size_t)tl_ * 64 * 32); if (TYPE == 0) cb##S = cg_[tl_ * 64]; } while (0)
; template <int TYPE, int ND0, int KSTR> __device__ __forceinline__ void tile(LAS unsigned char* lds, int buf, int t, int w_lo, int w_hi, int n, int qrel, int lane, int r32, int hi,
;         const bf16x8 (&qr)[ND0], float& m_run, float& l_run, f32x16& o0, f32x16& o1, f32x16& negm) {
;     ...
;         if (t == w_hi) {
; #pragma unroll
;             for (int r = 0; r < 16; ++r) { const int kr_ = crow(r, hi); if (kr_ > qrel) p0[r] = -1e30f; if (kr_ + 32 > qrel) p1[r] = -1e30f; }
; template <int TYPE> __device__ __forceinline__ int unit(const P& p, LAS unsigned char* lds, int b, int h, int qb, int wave0, bool pre, unsigned nx, int G,
;         u32x4& kA, u32x4& vA, u32x4& k2A, float& cbA, u32x4& kB, u32x4& vB, u32x4& k2B, float& cbB) {
;     ...
;     float m_run = 0.f, l_run = 0.f; f32x16 o0 = {}, o1 = {};
;     f32x16 negm;
; #pragma unroll
;     for (int r = 0; r < 16; ++r) negm[r] = 0.f;
;     if (!pre) { ATT_LOAD(u_lo, A); ATT_LOAD(u_lo + 1, B); }
;     ATT_STORE(0, A);
;     __syncthreads();
;     const int qrel = 32 * (w & 1) + r32;
;     int t = u_lo;
.LBB0_656:
	s_or_b64 exec, exec, s[0:1]
	v_lshrrev_b32_e32 v244, 2, v230
	v_lshlrev_b32_e32 v218, 2, v13
	v_and_or_b32 v2, v244, 3, v218
	s_waitcnt vmcnt(2)
	v_mad_u32_u24 v239, v2, s27, 0
	v_and_b32_e32 v2, 16, v230
	v_and_or_b32 v2, v180, 12, v2
	v_and_or_b32 v0, s2, 32, v12
	v_lshlrev_b32_e32 v243, 1, v2
	v_or_b32_e32 v2, 32, v218
	v_cmp_gt_u32_e64 s[46:47], v2, v0
	v_or_b32_e32 v2, 33, v218
	v_cmp_gt_u32_e64 s[48:49], v2, v0
	v_or_b32_e32 v2, 2, v218
	v_cmp_gt_u32_e64 s[50:51], v2, v0
	v_or_b32_e32 v2, 34, v218
	v_cmp_gt_u32_e64 s[52:53], v2, v0
	v_or_b32_e32 v2, 3, v218
	v_cmp_gt_u32_e64 s[54:55], v2, v0
	v_or_b32_e32 v2, 35, v218
	v_cmp_gt_u32_e64 s[56:57], v2, v0
	v_or_b32_e32 v2, 8, v218
	v_cmp_gt_u32_e64 s[58:59], v2, v0
	v_or_b32_e32 v2, 40, v218
	v_cmp_gt_u32_e64 s[60:61], v2, v0
	v_or_b32_e32 v2, 9, v218
	v_cmp_gt_u32_e64 s[62:63], v2, v0
	v_or_b32_e32 v2, 41, v218
	v_cmp_gt_u32_e64 s[64:65], v2, v0
	v_or_b32_e32 v2, 10, v218
	v_cmp_gt_u32_e64 s[66:67], v2, v0
	v_or_b32_e32 v2, 42, v218
	v_cmp_gt_u32_e64 s[68:69], v2, v0
	v_or_b32_e32 v2, 11, v218
	v_cmp_gt_u32_e64 s[70:71], v2, v0
	v_or_b32_e32 v2, 43, v218
	v_cmp_gt_u32_e64 s[74:75], v2, v0
	v_or_b32_e32 v2, 16, v218
	v_cmp_gt_u32_e64 s[76:77], v2, v0
	v_or_b32_e32 v2, 48, v218
	v_cmp_gt_u32_e64 s[78:79], v2, v0
	v_or_b32_e32 v2, 17, v218
	v_cmp_gt_u32_e64 s[80:81], v2, v0
	v_or_b32_e32 v2, 49, v218
	v_cmp_gt_u32_e64 s[82:83], v2, v0
	v_or_b32_e32 v2, 18, v218
	v_cmp_gt_u32_e64 s[84:85], v2, v0
	v_or_b32_e32 v2, 50, v218
	v_cmp_gt_u32_e64 s[86:87], v2, v0
	v_or_b32_e32 v2, 19, v218
	v_cmp_gt_u32_e64 s[88:89], v2, v0
	v_or_b32_e32 v2, 51, v218
	v_cmp_gt_u32_e64 s[90:91], v2, v0
	v_or_b32_e32 v2, 24, v218
	v_cmp_gt_u32_e64 s[92:93], v2, v0
	v_or_b32_e32 v2, 56, v218
	v_cmp_gt_u32_e64 s[94:95], v2, v0
	v_or_b32_e32 v2, 25, v218
	s_movk_i32 s0, 0x90
	v_cmp_gt_u32_e64 s[96:97], v2, v0
	v_or_b32_e32 v2, 57, v218
	v_mad_u32_u24 v173, v12, s0, 0
	v_cmp_gt_u32_e64 s[0:1], v2, v0
	v_or_b32_e32 v2, 26, v218
	v_cmp_gt_u32_e64 s[4:5], v2, v0
	v_or_b32_e32 v2, 58, v218
	v_cmp_gt_u32_e64 s[6:7], v2, v0
	v_or_b32_e32 v2, 27, v218
	v_lshlrev_b32_e32 v245, 3, v14
	s_ashr_i32 s3, s3, 7
	s_lshl_b32 s25, s33, 2
	v_cmp_gt_u32_e64 s[8:9], v2, v0
	v_or_b32_e32 v2, 59, v218
	s_lshl_b32 s2, s28, 2
	v_mov_b32_e32 v14, v1
	v_mov_b32_e32 v15, v1
	v_lshlrev_b64 v[176:177], 9, v[10:11]
	s_add_i32 s41, s3, s25
	v_cmp_gt_u32_e64 s[42:43], v218, v0
	v_cmp_lt_u32_e64 s[38:39], v218, v0
	v_cmp_gt_u32_e64 s[72:73], v2, v0
	s_add_i32 s3, s3, s2
	v_mov_b32_e32 v0, v1
	v_mov_b32_e32 v2, v1
	v_mov_b32_e32 v3, v1
	v_mov_b32_e32 v4, v1
	v_mov_b32_e32 v5, v1
	v_mov_b32_e32 v6, v1
	v_mov_b32_e32 v7, v1
	v_mov_b32_e32 v8, v1
	v_mov_b32_e32 v9, v1
	v_mov_b32_e32 v10, v1
	v_mov_b32_e32 v11, v1
	v_mov_b32_e32 v12, v1
	v_mov_b32_e32 v13, v1
	v_mov_b64_e32 v[46:47], v[14:15]
	v_mov_b64_e32 v[30:31], v[14:15]
	v_mov_b64_e32 v[62:63], v[14:15]
	v_add_u32_e32 v231, 0, v172
	s_waitcnt vmcnt(0)
	v_add_u32_e32 v246, s26, v250
	s_mov_b32 s28, 0
	s_sub_i32 s30, 0, s3
	v_mov_b32_e32 v178, 0
	s_mov_b32 s29, -2
	v_mov_b64_e32 v[44:45], v[12:13]
	v_mov_b64_e32 v[42:43], v[10:11]
	v_mov_b64_e32 v[40:41], v[8:9]
	v_mov_b64_e32 v[38:39], v[6:7]
	v_mov_b64_e32 v[36:37], v[4:5]
	v_mov_b64_e32 v[34:35], v[2:3]
	v_mov_b64_e32 v[32:33], v[0:1]
	v_mov_b64_e32 v[28:29], v[12:13]
	v_mov_b64_e32 v[26:27], v[10:11]
	v_mov_b64_e32 v[24:25], v[8:9]
	v_mov_b64_e32 v[22:23], v[6:7]
	v_mov_b64_e32 v[20:21], v[4:5]
	v_mov_b64_e32 v[18:19], v[2:3]
	v_mov_b64_e32 v[16:17], v[0:1]
	v_mov_b64_e32 v[60:61], v[12:13]
	v_mov_b64_e32 v[58:59], v[10:11]
	v_mov_b64_e32 v[56:57], v[8:9]
	v_mov_b64_e32 v[54:55], v[6:7]
	v_mov_b64_e32 v[52:53], v[4:5]
	v_mov_b64_e32 v[50:51], v[2:3]
	v_mov_b64_e32 v[48:49], v[0:1]
	v_mov_b32_e32 v181, 0
	s_waitcnt lgkmcnt(0)
	s_barrier

; #define ATT_LOAD(t, S) do { const int tl_ = (t) < u_hi ? (t) : u_hi;     \
;         k##S = *(const u32x4*)(kg + (size_t)tl_ * 64 * 512); v##S = *(const u32x4*)(vg + (size_t)tl_ * 64 * 512); \
;         if (TYPE == 1) k2##S = *(const u32x4*)(krg + (size_t)tl_ * 64 * 32); if (TYPE == 0) cb##S = cg_[tl_ * 64]; } while (0)
; template <int TYPE> __device__ __forceinline__ int unit(const P& p, LAS unsigned char* lds, int b, int h, int qb, int wave0, bool pre, unsigned nx, int G,
;         u32x4& kA, u32x4& vA, u32x4& k2A, float& cbA, u32x4& kB, u32x4& vB, u32x4& k2B, float& cbB) {
;     ...
;     float m_run = 0.f, l_run = 0.f; f32x16 o0 = {}, o1 = {};
;     f32x16 negm;
; #pragma unroll
;     for (int r = 0; r < 16; ++r) negm[r] = 0.f;
;     if (!pre) { ATT_LOAD(u_lo, A); ATT_LOAD(u_lo + 1, B); }
;     ATT_STORE(0, A);
;     __syncthreads();
;     const int qrel = 32 * (w & 1) + r32;
;     int t = u_lo;
;     ...
;         if (t == u_lo && tid == 0) tk[0] = G + (int)nx;
.LBB0_703:
	s_or_b64 exec, exec, s[4:5]
	v_lshlrev_b32_e32 v218, 2, v3
	v_and_b32_e32 v178, 63, v226
	v_mad_u32_u24 v227, v2, s10, 0
	v_and_or_b32 v2, v6, 3, v218
	s_movk_i32 s4, 0xc0
	v_mad_u32_u24 v228, v2, s4, 0
	v_and_b32_e32 v2, 16, v226
	v_lshlrev_b32_e32 v3, 2, v178
	v_and_or_b32 v2, v3, 12, v2
	v_mov_b32_e32 v14, v1
	v_mov_b32_e32 v15, v1
	v_lshlrev_b32_e32 v231, 3, v4
	v_lshlrev_b32_e32 v230, 3, v5
	s_ashr_i32 s9, s2, 7
	s_lshl_b32 s2, s33, 2
	v_lshlrev_b32_e32 v229, 1, v2
	v_add_u32_e32 v225, 0, v0
	v_mov_b32_e32 v0, v1
	v_mov_b32_e32 v2, v1
	v_mov_b32_e32 v3, v1
	v_mov_b32_e32 v4, v1
	v_mov_b32_e32 v5, v1
	v_mov_b32_e32 v6, v1
	v_mov_b32_e32 v7, v1
	v_mov_b32_e32 v8, v1
	v_mov_b32_e32 v9, v1
	v_mov_b32_e32 v10, v1
	v_mov_b32_e32 v11, v1
	v_mov_b32_e32 v12, v1
	v_mov_b32_e32 v13, v1
	v_mov_b64_e32 v[46:47], v[14:15]
	v_mov_b64_e32 v[30:31], v[14:15]
	v_mov_b64_e32 v[62:63], v[14:15]
	s_lshl_b32 s8, s24, 6
	s_add_i32 s9, s9, s2
	s_waitcnt vmcnt(0)
	v_add_u32_e32 v219, s26, v250
	s_mov_b32 s3, 0
	v_mov_b32_e32 v166, 0
	v_mov_b64_e32 v[44:45], v[12:13]
	v_mov_b64_e32 v[42:43], v[10:11]
	v_mov_b64_e32 v[40:41], v[8:9]
	v_mov_b64_e32 v[38:39], v[6:7]
	v_mov_b64_e32 v[36:37], v[4:5]
	v_mov_b64_e32 v[34:35], v[2:3]
	v_mov_b64_e32 v[32:33], v[0:1]
	v_mov_b64_e32 v[28:29], v[12:13]
	v_mov_b64_e32 v[26:27], v[10:11]
	v_mov_b64_e32 v[24:25], v[8:9]
	v_mov_b64_e32 v[22:23], v[6:7]
	v_mov_b64_e32 v[20:21], v[4:5]
	v_mov_b64_e32 v[18:19], v[2:3]
	v_mov_b64_e32 v[16:17], v[0:1]
	v_mov_b64_e32 v[60:61], v[12:13]
	v_mov_b64_e32 v[58:59], v[10:11]
	v_mov_b64_e32 v[56:57], v[8:9]
	v_mov_b64_e32 v[54:55], v[6:7]
	v_mov_b64_e32 v[52:53], v[4:5]
	v_mov_b64_e32 v[50:51], v[2:3]
	v_mov_b64_e32 v[48:49], v[0:1]
	v_mov_b32_e32 v171, 0
	s_waitcnt lgkmcnt(0)
	s_barrier

; __device__ __forceinline__ unsigned xb_add(unsigned* p, unsigned v) { return __hip_atomic_fetch_add(p, v, __ATOMIC_RELAXED, __HIP_MEMORY_SCOPE_AGENT); }
; __device__ __forceinline__ void xcd_barrier(const XcdBarrier& b, bool leader_thread) {
;     ...
;             __builtin_amdgcn_fence(__ATOMIC_ACQUIRE, "agent");
;             xb_add(&bar[XB_XGEN(b.x)], 1u);
;             asm volatile("s_waitcnt vmcnt(0)" ::: "memory");
.LBB0_794:
	s_or_b64 exec, exec, s[6:7]
	s_mov_b64 s[6:7], exec
	v_mbcnt_lo_u32_b32 v0, s6, 0
	v_mbcnt_hi_u32_b32 v0, s7, v0
	v_cmp_eq_u32_e32 vcc, 0, v0
	s_waitcnt vmcnt(0)
	s_and_saveexec_b64 s[8:9], vcc
	s_cbranch_execz .LBB0_796
	s_bcnt1_i32_b64 s3, s[6:7]
	v_readlane_b32 s6, v252, 55
	v_mov_b32_e32 v0, s3
	v_readlane_b32 s7, v252, 56
	s_nop 4
	global_atomic_add v1, v0, s[6:7]
.LBB0_796:
	s_or_b64 exec, exec, s[8:9]
	buffer_inv sc1
	s_waitcnt vmcnt(0)
